# gate/up GEMM tails (ph2, ph10): counted wait vmcnt(8) instead of vmcnt(0) (the 8 act stores are the only ops younger than the last LDS-DMA stages), on top of the relaxed in-phase syncs
# speedup vs baseline: 1.0040x; 1.0040x over previous
; #define PG8_WAIT_V(n) asm volatile("s_waitcnt vmcnt(" #n ")" ::: "memory")
; #define PG8_BAR __builtin_amdgcn_s_barrier()
; template <class Epi>
; __device__ __forceinline__ void gemm_phase(LAS unsigned char* lds, const Gemm g, const StaticOrder& S, const Epi& E) {
;     ...
;     PG8_WAIT_V(0);
;     if (wr == 0) PG8_BAR;
;     PG8_BAR;
.LBB0_1545:
	s_waitcnt vmcnt(8)
	s_cmpk_gt_u32 s3, 0xff
	s_cbranch_scc1 .LBB0_1547
	s_barrier
